# conversion split 9.2K prologue / 41K scan0 / 37.9K scan2 (3K gate-up items of layer 0 moved back to the prologue)
# speedup vs baseline: 1.0077x; 1.0077x over previous
; #define LAS __attribute__((address_space(3)))
; DI void phase_prologue(const Frame& F0, const Args& a) {
;     ...
;         LAS float* scr = (LAS float*)(F.lds + 43008 + F.wave * 8448);
;         const int gw = F.vcu * NWAVES + F.wave, NGW = F.G * NWAVES;
;         constexpr int I_IN = 32 * (GIN / 32), I_SQ = 32 * 64, I_GU = 32 * (2 * DFF / 32), I_DN = (DFF / 64) * 64;
;         constexpr int NITEMS = 2 * I_IN + 2 * I_SQ + 2 * I_SQ + DEPTH * I_GU + DEPTH * I_DN;
;         for (int it = gw; it < NITEMS; it += NGW) {
.LBB0_79:
	s_or_b64 exec, exec, s[8:9]
	s_lshl_b32 s0, s60, 3
	s_add_i32 s6, s0, s44
	s_cmp_gt_i32 s6, 0x1583f
	s_cbranch_scc1 .LBB0_11
	s_mov_b32 s90, s6
	s_mov_b32 s92, 0
	s_mov_b32 s91, 0x15840
	v_readlane_b32 s93, v252, 53
	s_cmp_eq_u32 s3, 0x100
	s_cbranch_scc0 .Lconv_entry
	s_mov_b32 s92, 1
	s_mov_b32 s91, 0x23d8

; DI void phase_prologue(const Frame& F0, const Args& a) {
;     ...
;         for (int it = gw; it < NITEMS; it += NGW) {
;             int r = it;
;             if (r < 2 * I_IN) { const int j = r / I_IN; r %= I_IN; const int nblk = GIN / 32, kb = r / nblk, nb = r % nblk;
;                 transpose_item(a.gla_w_in + (size_t)j * DM * GIN, DM, GIN, (bf16*)(ws + WS_WIN) + (size_t)j * GIN_PAD * DM, 64 * kb, 32 * nb, 32 * nb, scr, F.lane); continue; }
;             r -= 2 * I_IN;
;             if (r < 2 * I_SQ) { const int j = r / I_SQ; r %= I_SQ; const int kb = r / 64, nb = r % 64;
;                 transpose_item(a.gla_w_out + (size_t)j * DM * DM, DM, DM, (bf16*)(ws + WS_WGO) + (size_t)j * DM * DM, 64 * kb, 32 * nb, 32 * nb, scr, F.lane); continue; }
;             r -= 2 * I_SQ;
;             if (r < 2 * I_SQ) { const int j = r / I_SQ; r %= I_SQ; const int kb = r / 64, nb = r % 64;
;                 transpose_item(a.fnet_w_out + (size_t)j * DM * DM, DM, DM, (bf16*)(ws + WS_WFO) + (size_t)j * DM * DM, 64 * kb, 32 * nb, 32 * nb, scr, F.lane, 1); continue; }
;             r -= 2 * I_SQ;
;             if (r < DEPTH * I_GU) { const int j = r / I_GU; r %= I_GU; const int nblk = 2 * DFF / 32, kb = r / nblk, nb = r % nblk, n0 = 32 * nb;
;                 const int jj = n0 < DFF ? n0 : n0 - DFF; const int drow = (jj >> 7) * 256 + (n0 < DFF ? 0 : 128) + (jj & 127);
;                 transpose_item(a.ffn_w_gu + (size_t)j * DM * 2 * DFF, DM, 2 * DFF, (bf16*)(ws + WS_WGU) + (size_t)j * 2 * DFF * DM, 64 * kb, n0, drow, scr, F.lane); continue; }
;             r -= DEPTH * I_GU;
;             { const int j = r / I_DN; r %= I_DN; const int kb = r / 64, nb = r % 64;
;                 transpose_item(a.ffn_w_down + (size_t)j * DFF * DM, DFF, DM, (bf16*)(ws + WS_WDN) + (size_t)j * DM * DFF, 64 * kb, 32 * nb, 32 * nb, scr, F.lane); }
.Lcv_map1:
	s_mov_b32 s0, 0x5868
	s_cmp_lt_i32 s94, 0x1820
	s_cselect_b32 s0, 0x0, s0
	s_add_i32 s6, s94, s0
	s_branch .Lcv_mapped
.Lcv_map2:
	s_mov_b32 s0, 0x8bd8
	s_cmp_lt_i32 s94, 0x7468
	s_cselect_b32 s0, 0x33d8, s0
	s_cmp_lt_i32 s94, 0x4868
	s_cselect_b32 s0, 0x2820, s0
	s_cmp_lt_i32 s94, 0x2820
	s_cselect_b32 s0, 0x2020, s0
	s_cmp_lt_i32 s94, 0x2020
	s_cselect_b32 s0, 0x1820, s0
	s_add_i32 s6, s94, s0
	s_branch .Lcv_mapped

; DI void phase_prologue(const Frame& F0, const Args& a) {
;     ...
;         const int gw = F.vcu * NWAVES + F.wave, NGW = F.G * NWAVES;
;         constexpr int I_IN = 32 * (GIN / 32), I_SQ = 32 * 64, I_GU = 32 * (2 * DFF / 32), I_DN = (DFF / 64) * 64;
;         constexpr int NITEMS = 2 * I_IN + 2 * I_SQ + 2 * I_SQ + DEPTH * I_GU + DEPTH * I_DN;
;         for (int it = gw; it < NITEMS; it += NGW) {
; DI void phase_scan(const Frame& F0, const Args& a, int colmajor) {
;     ...
;     for (int it = F.vcu; it < 256; it += F.G) {
;         if ((it & 31) >= 16) continue;
.Lconv_scan_idle:
	s_cmp_eq_u32 s3, 0x100
	s_cbranch_scc0 .LBB0_821
	v_writelane_b32 v100, s11, 0
	v_writelane_b32 v100, s20, 1
	v_writelane_b32 v100, s21, 2
	v_writelane_b32 v100, s22, 3
	v_writelane_b32 v100, s26, 4
	v_writelane_b32 v100, s28, 5
	v_writelane_b32 v100, s29, 6
	v_writelane_b32 v100, s30, 7
	v_writelane_b32 v100, s44, 8
	v_writelane_b32 v100, s86, 9
	v_writelane_b32 v100, s87, 10
	v_mov_b32_e32 v101, v1
	v_mov_b32_e32 v102, v3
	v_readlane_b32 s0, v255, 17
	v_readlane_b32 s1, v252, 48
	v_readlane_b32 s44, v252, 49
	v_readlane_b32 s86, v252, 46
	v_readlane_b32 s87, v252, 47
	v_mov_b32_e32 v78, v222
	s_lshr_b32 s4, s1, 5
	s_lshl_b32 s4, s4, 4
	s_and_b32 s5, s1, 15
	s_or_b32 s4, s4, s5
	s_cmp_ge_u32 s44, 8
	s_cbranch_scc1 .Lconv_ret_scan
	s_mul_i32 s4, s4, 8
	s_add_i32 s90, s4, s44
	s_movk_i32 s93, 0x400
	s_mov_b32 s4, 0xa068
	s_mov_b32 s5, 0x9400
	s_cmp_eq_u32 s0, 0
	s_cselect_b32 s92, 2, 3
	s_cselect_b32 s91, s4, s5
	s_cmp_lt_i32 s90, s91
	s_cbranch_scc1 .Lconv_entry
